# lever 9 (7.11): MLA fast-loop back edge rotated out of the segment head (loop-back barrier becomes the loop head; V pointer step + branch before it)
# baseline (speedup 1.0000x reference)
; #define AT_QK_LD0(kb_) do { if constexpr (NEGM) { const LAS unsigned char* kbp_ = Kl + (kb_) * KBUF + r32 * KROWB + hi * 16; AT_KLD2(0); __builtin_amdgcn_sched_barrier(0); } } while (0)
; template <int DQK, int DV, int RH, bool NEGM> ...
;     ...
;     AT_GLOAD(0); AT_LSTORE(0, 0); __syncthreads();
;     int vs_prev = 2, vs_cur = 0, vs_next = 1;
;     if (!grpB) {
;         for (int t = 0; t < NT; ++t) {
;             const int kb = t & 1;
;             if (t + 1 < NT) AT_GLOAD(t + 1);
;             f32x16 p[RH][2];
;             AT_QK_LD0(kb); AT_QK(kb); AT_VLOAD(vs_cur); AT_SOFTMAX(); AT_PV(vs_cur);
;             if (t + 1 < NT) AT_LSTORE(kb ^ 1, vs_next);
;             __syncthreads();
;             vs_prev = vs_cur; vs_cur = vs_next; vs_next = (vs_next == 2) ? 0 : vs_next + 1;
.LBB0_881:
	s_or_b64 exec, exec, s[42:43]
	v_pk_add_f32 v[48:49], v[48:49], v[54:55]
	v_pk_add_f32 v[64:65], v[128:129], v[64:65]
	v_pk_add_f32 v[48:49], v[58:59], v[48:49] op_sel_hi:[0,1]
	v_pk_add_f32 v[52:53], v[52:53], v[56:57]
	v_pk_add_f32 v[48:49], v[64:65], v[48:49]
	v_pk_add_f32 v[70:71], v[118:119], v[70:71]
	v_pk_add_f32 v[48:49], v[52:53], v[48:49]
	v_add_u32_e32 v54, v136, v135
	v_pk_add_f32 v[150:151], v[70:71], v[48:49]
	v_add_u32_e32 v48, 0x8c00, v166
	s_waitcnt vmcnt(0)
	ds_write2_b64 v48, v[74:75], v[76:77] offset1:2
	v_mul_lo_u32 v48, v54, 12
	v_sub_u32_e32 v52, v133, v48
	s_lshr_b32 s21, s61, 4
	v_lshlrev_b32_e32 v48, 3, v52
	v_lshlrev_b32_e32 v175, 4, v52
	v_mov_b64_e32 v[52:53], s[40:41]
	s_and_b32 s42, s21, 7
	v_mul_lo_u32 v174, v54, s56
	v_mad_i64_i32 v[54:55], s[40:41], v54, s51, v[52:53]
	v_pk_add_f32 v[50:51], v[50:51], v[62:63]
	v_ashrrev_i32_e32 v49, 31, v48
	v_mad_u64_u32 v[54:55], s[40:41], s42, v163, v[54:55]
	v_pk_add_f32 v[66:67], v[130:131], v[66:67]
	v_pk_add_f32 v[50:51], v[58:59], v[50:51] op_sel_hi:[0,1]
	v_lshl_add_u64 v[48:49], v[48:49], 1, v[54:55]
	v_pk_add_f32 v[56:57], v[116:117], v[68:69]
	v_pk_add_f32 v[50:51], v[66:67], v[50:51]
	v_mov_b32_e32 v154, v48
	v_mad_i64_i32 v[48:49], s[40:41], v59, s51, v[52:53]
	v_pk_add_f32 v[60:61], v[60:61], v[72:73]
	v_pk_add_f32 v[50:51], v[56:57], v[50:51]
	s_lshl_b32 s43, s42, 6
	v_mad_u64_u32 v[48:49], s[40:41], s42, v163, v[48:49]
	v_pk_add_f32 v[152:153], v[60:61], v[50:51]
	v_lshlrev_b32_e32 v50, 3, v112
	s_add_i32 s40, s47, s43
	v_ashrrev_i32_e32 v51, 31, v50
	s_ashr_i32 s41, s40, 31
	v_lshl_add_u64 v[48:49], v[50:51], 1, v[48:49]
	s_lshl_b64 s[40:41], s[40:41], 13
	v_and_b32_e32 v50, 7, v132
	v_mov_b32_e32 v156, v48
	v_lshl_add_u64 v[48:49], v[78:79], 0, s[40:41]
	v_lshlrev_b32_e32 v148, 4, v50
	v_lshl_add_u64 v[48:49], v[48:49], 0, v[148:149]
	v_mul_u32_u24_e32 v173, 0x90, v134
	s_mov_b32 s21, 1
	v_mov_b32_e32 v158, v48
	s_mov_b32 s42, 2
	s_mov_b32 s43, 1
	s_waitcnt lgkmcnt(0)
	s_barrier
	s_mov_b64 s[98:99], s[28:29]
	s_mov_b64 s[100:101], s[30:31]
	v_add_u32_e32 v244, v174, v175
	v_add_u32_e32 v245, v171, v172
	v_add_u32_e32 v241, v238, v154
	v_add_u32_e32 v242, v239, v156
	s_lshl_b32 s70, s79, 4
	s_add_i32 s73, s70, 0x2000
	s_cmpk_lt_u32 s79, 0x140
	s_cselect_b32 s73, s73, 0x12000
	s_cselect_b32 s74, 0x3400, 0
	s_cmp_eq_u32 s65, 0
	s_cbranch_scc0 .Lmlac_loop
	s_branch .Lmla_entry
.Lmla_loop:
	s_barrier
.Lmla_entry:
	ds_read_b128 v[48:51], v169 offset:13312
	ds_read_b128 v[52:55], v169 offset:13344
	ds_read_b128 v[116:119], v169 offset:19968
	ds_read_b128 v[120:123], v169 offset:20000
	s_mov_b32 m0, s70
	s_nop 0
	global_load_lds_dwordx4 v241, s[98:99]
	s_mov_b32 m0, s73
	global_load_dwordx4 v[112:115], v158, s[100:101]
	global_load_lds_dwordx4 v242, s[98:99]
	s_add_u32 s98, s98, 0x18000
	s_addc_u32 s99, s99, 0
	s_waitcnt lgkmcnt(3)
	v_mfma_f32_32x32x16_bf16 v[64:79], v[48:51], v[100:103], v[32:47]
	ds_read_b128 v[124:127], v169 offset:13376
	ds_read_b128 v[128:131], v169 offset:13408
	ds_read_b128 v[132:135], v169 offset:20032
	ds_read_b128 v[136:139], v169 offset:20064
	s_waitcnt lgkmcnt(4)
	v_mfma_f32_32x32x16_bf16 v[64:79], v[52:55], v[96:99], v[64:79]
	v_mfma_f32_32x32x16_bf16 v[48:63], v[116:119], v[100:103], v[32:47]
	v_mfma_f32_32x32x16_bf16 v[48:63], v[120:123], v[96:99], v[48:63]
	s_waitcnt lgkmcnt(1)
	v_mfma_f32_32x32x16_bf16 v[64:79], v[124:127], v[92:95], v[64:79]
	v_mfma_f32_32x32x16_bf16 v[48:63], v[132:135], v[92:95], v[48:63]
	v_mfma_f32_32x32x16_bf16 v[64:79], v[128:131], v[88:91], v[64:79]
	ds_read_b128 v[116:119], v169 offset:13440
	ds_read_b128 v[120:123], v169 offset:13472
	ds_read_b128 v[128:131], v169 offset:20096
	ds_read_b128 v[176:179], v169 offset:20128
	s_waitcnt lgkmcnt(3)
	v_mfma_f32_32x32x16_bf16 v[48:63], v[136:139], v[88:91], v[48:63]
	v_mfma_f32_32x32x16_bf16 v[64:79], v[116:119], v[84:87], v[64:79]
	ds_read_b128 v[136:139], v170 offset:35840
	ds_read_b128 v[124:127], v170 offset:35872
	s_waitcnt lgkmcnt(3)
	v_mfma_f32_32x32x16_bf16 v[48:63], v[128:131], v[84:87], v[48:63]
	v_mfma_f32_32x32x16_bf16 v[64:79], v[120:123], v[80:83], v[64:79]
	ds_read_b128 v[132:135], v170 offset:35904
	ds_read_b128 v[120:123], v170 offset:35936
	ds_read_b128 v[144:147], v170 offset:40448
	ds_read_b128 v[140:143], v170 offset:40480
	ds_read_b128 v[128:131], v170 offset:40512
	ds_read_b128 v[116:119], v170 offset:40544
	s_waitcnt lgkmcnt(8)
	v_mfma_f32_32x32x16_bf16 v[48:63], v[176:179], v[80:83], v[48:63]
	s_add_i32 s43, s43, 1
	s_nop 3
	v_exp_f32_e32 v160, v64
	v_exp_f32_e32 v161, v65
	v_exp_f32_e32 v64, v66
	v_exp_f32_e32 v65, v67
	v_exp_f32_e32 v68, v68
	v_exp_f32_e32 v69, v69
	v_exp_f32_e32 v66, v70
	v_exp_f32_e32 v67, v71
	v_cvt_pk_bf16_f32 v176, v160, v161
	v_cvt_pk_bf16_f32 v177, v64, v65
	v_cvt_pk_bf16_f32 v178, v68, v69
	v_cvt_pk_bf16_f32 v179, v66, v67
	v_exp_f32_e32 v70, v74
	v_exp_f32_e32 v71, v75
	s_waitcnt lgkmcnt(0)
; #define AT_QK_LD0(kb_) do { if constexpr (NEGM) { const LAS unsigned char* kbp_ = Kl + (kb_) * KBUF + r32 * KROWB + hi * 16; AT_KLD2(0); __builtin_amdgcn_sched_barrier(0); } } while (0)
; template <int DQK, int DV, int RH, bool NEGM> ...
;     ...
;         for (int t = 0; t < NT; ++t) {
;             const int kb = t & 1;
;             if (t + 1 < NT) AT_GLOAD(t + 1);
;             f32x16 p[RH][2];
;             AT_QK_LD0(kb); AT_QK(kb); AT_VLOAD(vs_cur); AT_SOFTMAX(); AT_PV(vs_cur);
;             if (t + 1 < NT) AT_LSTORE(kb ^ 1, vs_next);
;             __syncthreads();
;             vs_prev = vs_cur; vs_cur = vs_next; vs_next = (vs_next == 2) ? 0 : vs_next + 1;
	v_mfma_f32_32x32x16_bf16 v[16:31], v[136:139], v[176:179], v[16:31]
	v_exp_f32_e32 v136, v72
	v_exp_f32_e32 v137, v73
	v_exp_f32_e32 v74, v76
	v_exp_f32_e32 v75, v77
	v_exp_f32_e32 v72, v78
	v_exp_f32_e32 v73, v79
	v_exp_f32_e32 v76, v48
	v_mfma_f32_32x32x16_bf16 v[0:15], v[144:147], v[176:179], v[0:15]
	v_cvt_pk_bf16_f32 v144, v136, v137
	v_cvt_pk_bf16_f32 v145, v70, v71
	v_cvt_pk_bf16_f32 v146, v74, v75
	v_cvt_pk_bf16_f32 v147, v72, v73
	v_exp_f32_e32 v77, v49
	v_exp_f32_e32 v48, v50
	v_exp_f32_e32 v49, v51
	v_mfma_f32_32x32x16_bf16 v[16:31], v[124:127], v[144:147], v[16:31]
	v_exp_f32_e32 v52, v52
	v_exp_f32_e32 v53, v53
	v_exp_f32_e32 v50, v54
	v_exp_f32_e32 v51, v55
	v_cvt_pk_bf16_f32 v124, v76, v77
	v_cvt_pk_bf16_f32 v125, v48, v49
	v_cvt_pk_bf16_f32 v126, v52, v53
	v_mfma_f32_32x32x16_bf16 v[0:15], v[140:143], v[144:147], v[0:15]
	v_cvt_pk_bf16_f32 v127, v50, v51
	v_exp_f32_e32 v78, v56
	v_exp_f32_e32 v79, v57
	v_exp_f32_e32 v54, v58
	v_exp_f32_e32 v55, v59
	v_exp_f32_e32 v58, v60
	v_exp_f32_e32 v59, v61
	v_mfma_f32_32x32x16_bf16 v[16:31], v[132:135], v[124:127], v[16:31]
	v_exp_f32_e32 v56, v62
	v_exp_f32_e32 v57, v63
	v_cvt_pk_bf16_f32 v60, v78, v79
	v_cvt_pk_bf16_f32 v61, v54, v55
	v_cvt_pk_bf16_f32 v62, v58, v59
	v_cvt_pk_bf16_f32 v63, v56, v57
	v_mfma_f32_32x32x16_bf16 v[0:15], v[128:131], v[124:127], v[0:15]
	v_mfma_f32_32x32x16_bf16 v[16:31], v[120:123], v[60:63], v[16:31]
	v_mfma_f32_32x32x16_bf16 v[0:15], v[116:119], v[60:63], v[0:15]
	s_waitcnt vmcnt(0)
	ds_write2_b64 v247, v[112:113], v[114:115] offset1:2
	v_pk_add_f32 v[48:49], v[64:65], v[48:49]
	v_pk_add_f32 v[60:61], v[160:161], v[76:77]
	v_pk_add_f32 v[48:49], v[152:153], v[48:49]
	v_pk_add_f32 v[50:51], v[66:67], v[50:51]
	v_pk_add_f32 v[60:61], v[150:151], v[60:61]
	v_pk_add_f32 v[52:53], v[68:69], v[52:53]
	v_pk_add_f32 v[48:49], v[50:51], v[48:49]
	v_pk_add_f32 v[50:51], v[70:71], v[54:55]
	v_pk_add_f32 v[52:53], v[52:53], v[60:61]
	v_pk_add_f32 v[60:61], v[136:137], v[78:79]
	v_pk_add_f32 v[48:49], v[50:51], v[48:49]
	v_pk_add_f32 v[50:51], v[72:73], v[56:57]
	v_pk_add_f32 v[52:53], v[60:61], v[52:53]
	v_pk_add_f32 v[58:59], v[74:75], v[58:59]
	v_pk_add_f32 v[152:153], v[50:51], v[48:49]
	v_pk_add_f32 v[150:151], v[58:59], v[52:53]
	s_waitcnt lgkmcnt(0)
	s_barrier
	ds_read_b128 v[48:51], v169
	ds_read_b128 v[52:55], v169 offset:32
	ds_read_b128 v[116:119], v169 offset:6656
	ds_read_b128 v[120:123], v169 offset:6688
	s_add_i32 m0, s70, 13312
	s_nop 0
	global_load_lds_dwordx4 v241, s[98:99]
	s_add_i32 m0, s73, s74
	global_load_dwordx4 v[112:115], v158, s[100:101] offset:128
	global_load_lds_dwordx4 v242, s[98:99]
	s_add_u32 s98, s98, 0x18000
	s_addc_u32 s99, s99, 0
	s_waitcnt lgkmcnt(3)
	v_mfma_f32_32x32x16_bf16 v[64:79], v[48:51], v[100:103], v[32:47]
	ds_read_b128 v[124:127], v169 offset:64
	ds_read_b128 v[128:131], v169 offset:96
	ds_read_b128 v[132:135], v169 offset:6720
	ds_read_b128 v[136:139], v169 offset:6752
	s_waitcnt lgkmcnt(4)
	v_mfma_f32_32x32x16_bf16 v[64:79], v[52:55], v[96:99], v[64:79]
	v_mfma_f32_32x32x16_bf16 v[48:63], v[116:119], v[100:103], v[32:47]
	v_mfma_f32_32x32x16_bf16 v[48:63], v[120:123], v[96:99], v[48:63]
	s_waitcnt lgkmcnt(1)
	v_mfma_f32_32x32x16_bf16 v[64:79], v[124:127], v[92:95], v[64:79]
	v_mfma_f32_32x32x16_bf16 v[48:63], v[132:135], v[92:95], v[48:63]
	v_mfma_f32_32x32x16_bf16 v[64:79], v[128:131], v[88:91], v[64:79]
	ds_read_b128 v[116:119], v169 offset:128
	ds_read_b128 v[120:123], v169 offset:160
	ds_read_b128 v[128:131], v169 offset:6784
	ds_read_b128 v[176:179], v169 offset:6816
	s_waitcnt lgkmcnt(3)
	v_mfma_f32_32x32x16_bf16 v[48:63], v[136:139], v[88:91], v[48:63]
	v_mfma_f32_32x32x16_bf16 v[64:79], v[116:119], v[84:87], v[64:79]
	ds_read_b128 v[136:139], v170 offset:45056
	ds_read_b128 v[124:127], v170 offset:45088
	s_waitcnt lgkmcnt(3)
	v_mfma_f32_32x32x16_bf16 v[48:63], v[128:131], v[84:87], v[48:63]
	v_mfma_f32_32x32x16_bf16 v[64:79], v[120:123], v[80:83], v[64:79]
	ds_read_b128 v[132:135], v170 offset:45120
	ds_read_b128 v[120:123], v170 offset:45152
	ds_read_b128 v[144:147], v170 offset:49664
	ds_read_b128 v[140:143], v170 offset:49696
	ds_read_b128 v[128:131], v170 offset:49728
	ds_read_b128 v[116:119], v170 offset:49760
	s_waitcnt lgkmcnt(8)
	v_mfma_f32_32x32x16_bf16 v[48:63], v[176:179], v[80:83], v[48:63]
	s_add_i32 s43, s43, 1
	s_nop 3
	v_exp_f32_e32 v160, v64
	v_exp_f32_e32 v161, v65
	v_exp_f32_e32 v64, v66
	v_exp_f32_e32 v65, v67
	v_exp_f32_e32 v68, v68
	v_exp_f32_e32 v69, v69
	v_exp_f32_e32 v66, v70
	v_exp_f32_e32 v67, v71
	v_cvt_pk_bf16_f32 v176, v160, v161
	v_cvt_pk_bf16_f32 v177, v64, v65
	v_cvt_pk_bf16_f32 v178, v68, v69
	v_cvt_pk_bf16_f32 v179, v66, v67
	v_exp_f32_e32 v70, v74
	v_exp_f32_e32 v71, v75
	s_waitcnt lgkmcnt(0)
	v_mfma_f32_32x32x16_bf16 v[16:31], v[136:139], v[176:179], v[16:31]
	v_exp_f32_e32 v136, v72
	v_exp_f32_e32 v137, v73
	v_exp_f32_e32 v74, v76
	v_exp_f32_e32 v75, v77
	v_exp_f32_e32 v72, v78
	v_exp_f32_e32 v73, v79
	v_exp_f32_e32 v76, v48
	v_mfma_f32_32x32x16_bf16 v[0:15], v[144:147], v[176:179], v[0:15]
	v_cvt_pk_bf16_f32 v144, v136, v137
	v_cvt_pk_bf16_f32 v145, v70, v71
	v_cvt_pk_bf16_f32 v146, v74, v75
	v_cvt_pk_bf16_f32 v147, v72, v73
	v_exp_f32_e32 v77, v49
	v_exp_f32_e32 v48, v50
	v_exp_f32_e32 v49, v51
	v_mfma_f32_32x32x16_bf16 v[16:31], v[124:127], v[144:147], v[16:31]
	v_exp_f32_e32 v52, v52
	v_exp_f32_e32 v53, v53
	v_exp_f32_e32 v50, v54
	v_exp_f32_e32 v51, v55
	v_cvt_pk_bf16_f32 v124, v76, v77
	v_cvt_pk_bf16_f32 v125, v48, v49
	v_cvt_pk_bf16_f32 v126, v52, v53
	v_mfma_f32_32x32x16_bf16 v[0:15], v[140:143], v[144:147], v[0:15]
	v_cvt_pk_bf16_f32 v127, v50, v51
	v_exp_f32_e32 v78, v56
	v_exp_f32_e32 v79, v57
	v_exp_f32_e32 v54, v58
	v_exp_f32_e32 v55, v59
	v_exp_f32_e32 v58, v60
	v_exp_f32_e32 v59, v61
	v_mfma_f32_32x32x16_bf16 v[16:31], v[132:135], v[124:127], v[16:31]
	v_exp_f32_e32 v56, v62
	v_exp_f32_e32 v57, v63
	v_cvt_pk_bf16_f32 v60, v78, v79
	v_cvt_pk_bf16_f32 v61, v54, v55
	v_cvt_pk_bf16_f32 v62, v58, v59
	v_cvt_pk_bf16_f32 v63, v56, v57
	v_mfma_f32_32x32x16_bf16 v[0:15], v[128:131], v[124:127], v[0:15]
	v_mfma_f32_32x32x16_bf16 v[16:31], v[120:123], v[60:63], v[16:31]
	v_mfma_f32_32x32x16_bf16 v[0:15], v[116:119], v[60:63], v[0:15]
	s_waitcnt vmcnt(0)
; #define AT_QK_LD0(kb_) do { if constexpr (NEGM) { const LAS unsigned char* kbp_ = Kl + (kb_) * KBUF + r32 * KROWB + hi * 16; AT_KLD2(0); __builtin_amdgcn_sched_barrier(0); } } while (0)
; template <int DQK, int DV, int RH, bool NEGM> ...
;     ...
;         for (int t = 0; t < NT; ++t) {
;             const int kb = t & 1;
;             if (t + 1 < NT) AT_GLOAD(t + 1);
;             f32x16 p[RH][2];
;             AT_QK_LD0(kb); AT_QK(kb); AT_VLOAD(vs_cur); AT_SOFTMAX(); AT_PV(vs_cur);
;             if (t + 1 < NT) AT_LSTORE(kb ^ 1, vs_next);
;             __syncthreads();
;             vs_prev = vs_cur; vs_cur = vs_next; vs_next = (vs_next == 2) ? 0 : vs_next + 1;
	ds_write2_b64 v243, v[112:113], v[114:115] offset1:2
	v_pk_add_f32 v[48:49], v[64:65], v[48:49]
	v_pk_add_f32 v[60:61], v[160:161], v[76:77]
	v_pk_add_f32 v[48:49], v[152:153], v[48:49]
	v_pk_add_f32 v[50:51], v[66:67], v[50:51]
	v_pk_add_f32 v[60:61], v[150:151], v[60:61]
	v_pk_add_f32 v[52:53], v[68:69], v[52:53]
	v_pk_add_f32 v[48:49], v[50:51], v[48:49]
	v_pk_add_f32 v[50:51], v[70:71], v[54:55]
	v_pk_add_f32 v[52:53], v[52:53], v[60:61]
	v_pk_add_f32 v[60:61], v[136:137], v[78:79]
	v_pk_add_f32 v[48:49], v[50:51], v[48:49]
	v_pk_add_f32 v[50:51], v[72:73], v[56:57]
	v_pk_add_f32 v[52:53], v[60:61], v[52:53]
	v_pk_add_f32 v[58:59], v[74:75], v[58:59]
	v_pk_add_f32 v[152:153], v[50:51], v[48:49]
	v_pk_add_f32 v[150:151], v[58:59], v[52:53]
	s_cmp_lg_u32 s43, 63
	s_waitcnt lgkmcnt(0)
	s_barrier
	s_cbranch_scc0 .Lmla_exit
	ds_read_b128 v[48:51], v169 offset:13312
	ds_read_b128 v[52:55], v169 offset:13344
	ds_read_b128 v[116:119], v169 offset:19968
	ds_read_b128 v[120:123], v169 offset:20000
	s_mov_b32 m0, s70
	s_nop 0
	global_load_lds_dwordx4 v241, s[98:99]
	s_mov_b32 m0, s73
	global_load_dwordx4 v[112:115], v158, s[100:101] offset:256
	global_load_lds_dwordx4 v242, s[98:99]
	s_add_u32 s98, s98, 0x18000
	s_addc_u32 s99, s99, 0
	s_waitcnt lgkmcnt(3)
	v_mfma_f32_32x32x16_bf16 v[64:79], v[48:51], v[100:103], v[32:47]
	ds_read_b128 v[124:127], v169 offset:13376
	ds_read_b128 v[128:131], v169 offset:13408
	ds_read_b128 v[132:135], v169 offset:20032
	ds_read_b128 v[136:139], v169 offset:20064
	s_waitcnt lgkmcnt(4)
	v_mfma_f32_32x32x16_bf16 v[64:79], v[52:55], v[96:99], v[64:79]
	v_mfma_f32_32x32x16_bf16 v[48:63], v[116:119], v[100:103], v[32:47]
	v_mfma_f32_32x32x16_bf16 v[48:63], v[120:123], v[96:99], v[48:63]
	s_waitcnt lgkmcnt(1)
	v_mfma_f32_32x32x16_bf16 v[64:79], v[124:127], v[92:95], v[64:79]
	v_mfma_f32_32x32x16_bf16 v[48:63], v[132:135], v[92:95], v[48:63]
	v_mfma_f32_32x32x16_bf16 v[64:79], v[128:131], v[88:91], v[64:79]
	ds_read_b128 v[116:119], v169 offset:13440
	ds_read_b128 v[120:123], v169 offset:13472
	ds_read_b128 v[128:131], v169 offset:20096
	ds_read_b128 v[176:179], v169 offset:20128
	s_waitcnt lgkmcnt(3)
	v_mfma_f32_32x32x16_bf16 v[48:63], v[136:139], v[88:91], v[48:63]
	v_mfma_f32_32x32x16_bf16 v[64:79], v[116:119], v[84:87], v[64:79]
	ds_read_b128 v[136:139], v170 offset:26624
	ds_read_b128 v[124:127], v170 offset:26656
	s_waitcnt lgkmcnt(3)
	v_mfma_f32_32x32x16_bf16 v[48:63], v[128:131], v[84:87], v[48:63]
	v_mfma_f32_32x32x16_bf16 v[64:79], v[120:123], v[80:83], v[64:79]
	ds_read_b128 v[132:135], v170 offset:26688
	ds_read_b128 v[120:123], v170 offset:26720
	ds_read_b128 v[144:147], v170 offset:31232
	ds_read_b128 v[140:143], v170 offset:31264
	ds_read_b128 v[128:131], v170 offset:31296
	ds_read_b128 v[116:119], v170 offset:31328
	s_waitcnt lgkmcnt(8)
	v_mfma_f32_32x32x16_bf16 v[48:63], v[176:179], v[80:83], v[48:63]
	s_add_i32 s43, s43, 1
	s_nop 3
	v_exp_f32_e32 v160, v64
	v_exp_f32_e32 v161, v65
	v_exp_f32_e32 v64, v66
	v_exp_f32_e32 v65, v67
	v_exp_f32_e32 v68, v68
	v_exp_f32_e32 v69, v69
	v_exp_f32_e32 v66, v70
	v_exp_f32_e32 v67, v71
	v_cvt_pk_bf16_f32 v176, v160, v161
	v_cvt_pk_bf16_f32 v177, v64, v65
	v_cvt_pk_bf16_f32 v178, v68, v69
	v_cvt_pk_bf16_f32 v179, v66, v67
	v_exp_f32_e32 v70, v74
	v_exp_f32_e32 v71, v75
	s_waitcnt lgkmcnt(0)
	v_mfma_f32_32x32x16_bf16 v[16:31], v[136:139], v[176:179], v[16:31]
	v_exp_f32_e32 v136, v72
	v_exp_f32_e32 v137, v73
	v_exp_f32_e32 v74, v76
	v_exp_f32_e32 v75, v77
	v_exp_f32_e32 v72, v78
	v_exp_f32_e32 v73, v79
	v_exp_f32_e32 v76, v48
	v_mfma_f32_32x32x16_bf16 v[0:15], v[144:147], v[176:179], v[0:15]
	v_cvt_pk_bf16_f32 v144, v136, v137
	v_cvt_pk_bf16_f32 v145, v70, v71
	v_cvt_pk_bf16_f32 v146, v74, v75
	v_cvt_pk_bf16_f32 v147, v72, v73
	v_exp_f32_e32 v77, v49
	v_exp_f32_e32 v48, v50
	v_exp_f32_e32 v49, v51
	v_mfma_f32_32x32x16_bf16 v[16:31], v[124:127], v[144:147], v[16:31]
	v_exp_f32_e32 v52, v52
	v_exp_f32_e32 v53, v53
	v_exp_f32_e32 v50, v54
	v_exp_f32_e32 v51, v55
	v_cvt_pk_bf16_f32 v124, v76, v77
	v_cvt_pk_bf16_f32 v125, v48, v49
	v_cvt_pk_bf16_f32 v126, v52, v53
	v_mfma_f32_32x32x16_bf16 v[0:15], v[140:143], v[144:147], v[0:15]
	v_cvt_pk_bf16_f32 v127, v50, v51
	v_exp_f32_e32 v78, v56
	v_exp_f32_e32 v79, v57
	v_exp_f32_e32 v54, v58
	v_exp_f32_e32 v55, v59
	v_exp_f32_e32 v58, v60
	v_exp_f32_e32 v59, v61
	v_mfma_f32_32x32x16_bf16 v[16:31], v[132:135], v[124:127], v[16:31]
	v_exp_f32_e32 v56, v62
	v_exp_f32_e32 v57, v63
	v_cvt_pk_bf16_f32 v60, v78, v79
	v_cvt_pk_bf16_f32 v61, v54, v55
	v_cvt_pk_bf16_f32 v62, v58, v59
	v_cvt_pk_bf16_f32 v63, v56, v57
	v_mfma_f32_32x32x16_bf16 v[0:15], v[128:131], v[124:127], v[0:15]
	v_mfma_f32_32x32x16_bf16 v[16:31], v[120:123], v[60:63], v[16:31]
	v_mfma_f32_32x32x16_bf16 v[0:15], v[116:119], v[60:63], v[0:15]
	s_waitcnt vmcnt(0)
	ds_write2_b64 v246, v[112:113], v[114:115] offset1:2
	v_pk_add_f32 v[48:49], v[64:65], v[48:49]
	v_pk_add_f32 v[60:61], v[160:161], v[76:77]
	v_pk_add_f32 v[48:49], v[152:153], v[48:49]
	v_pk_add_f32 v[50:51], v[66:67], v[50:51]
	v_pk_add_f32 v[60:61], v[150:151], v[60:61]
	v_pk_add_f32 v[52:53], v[68:69], v[52:53]
	v_pk_add_f32 v[48:49], v[50:51], v[48:49]
	v_pk_add_f32 v[50:51], v[70:71], v[54:55]
	v_pk_add_f32 v[52:53], v[52:53], v[60:61]
	v_pk_add_f32 v[60:61], v[136:137], v[78:79]
	v_pk_add_f32 v[48:49], v[50:51], v[48:49]
	v_pk_add_f32 v[50:51], v[72:73], v[56:57]
	v_pk_add_f32 v[52:53], v[60:61], v[52:53]
	v_pk_add_f32 v[58:59], v[74:75], v[58:59]
	v_pk_add_f32 v[152:153], v[50:51], v[48:49]
	v_pk_add_f32 v[150:151], v[58:59], v[52:53]
	s_waitcnt lgkmcnt(0)
	s_barrier
; #define AT_QK_LD0(kb_) do { if constexpr (NEGM) { const LAS unsigned char* kbp_ = Kl + (kb_) * KBUF + r32 * KROWB + hi * 16; AT_KLD2(0); __builtin_amdgcn_sched_barrier(0); } } while (0)
; template <int DQK, int DV, int RH, bool NEGM> ...
;     ...
;         for (int t = 0; t < NT; ++t) {
;             const int kb = t & 1;
;             if (t + 1 < NT) AT_GLOAD(t + 1);
;             f32x16 p[RH][2];
;             AT_QK_LD0(kb); AT_QK(kb); AT_VLOAD(vs_cur); AT_SOFTMAX(); AT_PV(vs_cur);
;             if (t + 1 < NT) AT_LSTORE(kb ^ 1, vs_next);
;             __syncthreads();
;             vs_prev = vs_cur; vs_cur = vs_next; vs_next = (vs_next == 2) ? 0 : vs_next + 1;
	ds_read_b128 v[48:51], v169
	ds_read_b128 v[52:55], v169 offset:32
	ds_read_b128 v[116:119], v169 offset:6656
	ds_read_b128 v[120:123], v169 offset:6688
	s_add_i32 m0, s70, 13312
	s_nop 0
	global_load_lds_dwordx4 v241, s[98:99]
	s_add_i32 m0, s73, s74
	global_load_dwordx4 v[112:115], v158, s[100:101] offset:384
	global_load_lds_dwordx4 v242, s[98:99]
	s_add_u32 s98, s98, 0x18000
	s_addc_u32 s99, s99, 0
	s_waitcnt lgkmcnt(3)
	v_mfma_f32_32x32x16_bf16 v[64:79], v[48:51], v[100:103], v[32:47]
	ds_read_b128 v[124:127], v169 offset:64
	ds_read_b128 v[128:131], v169 offset:96
	ds_read_b128 v[132:135], v169 offset:6720
	ds_read_b128 v[136:139], v169 offset:6752
	s_waitcnt lgkmcnt(4)
	v_mfma_f32_32x32x16_bf16 v[64:79], v[52:55], v[96:99], v[64:79]
	v_mfma_f32_32x32x16_bf16 v[48:63], v[116:119], v[100:103], v[32:47]
	v_mfma_f32_32x32x16_bf16 v[48:63], v[120:123], v[96:99], v[48:63]
	s_waitcnt lgkmcnt(1)
	v_mfma_f32_32x32x16_bf16 v[64:79], v[124:127], v[92:95], v[64:79]
	v_mfma_f32_32x32x16_bf16 v[48:63], v[132:135], v[92:95], v[48:63]
	v_mfma_f32_32x32x16_bf16 v[64:79], v[128:131], v[88:91], v[64:79]
	ds_read_b128 v[116:119], v169 offset:128
	ds_read_b128 v[120:123], v169 offset:160
	ds_read_b128 v[128:131], v169 offset:6784
	ds_read_b128 v[176:179], v169 offset:6816
	s_waitcnt lgkmcnt(3)
	v_mfma_f32_32x32x16_bf16 v[48:63], v[136:139], v[88:91], v[48:63]
	v_mfma_f32_32x32x16_bf16 v[64:79], v[116:119], v[84:87], v[64:79]
	ds_read_b128 v[136:139], v170 offset:35840
	ds_read_b128 v[124:127], v170 offset:35872
	s_waitcnt lgkmcnt(3)
	v_mfma_f32_32x32x16_bf16 v[48:63], v[128:131], v[84:87], v[48:63]
	v_mfma_f32_32x32x16_bf16 v[64:79], v[120:123], v[80:83], v[64:79]
	ds_read_b128 v[132:135], v170 offset:35904
	ds_read_b128 v[120:123], v170 offset:35936
	ds_read_b128 v[144:147], v170 offset:40448
	ds_read_b128 v[140:143], v170 offset:40480
	ds_read_b128 v[128:131], v170 offset:40512
	ds_read_b128 v[116:119], v170 offset:40544
	s_waitcnt lgkmcnt(8)
	v_mfma_f32_32x32x16_bf16 v[48:63], v[176:179], v[80:83], v[48:63]
	s_add_i32 s43, s43, 1
	s_nop 3
	v_exp_f32_e32 v160, v64
	v_exp_f32_e32 v161, v65
	v_exp_f32_e32 v64, v66
	v_exp_f32_e32 v65, v67
	v_exp_f32_e32 v68, v68
	v_exp_f32_e32 v69, v69
	v_exp_f32_e32 v66, v70
	v_exp_f32_e32 v67, v71
	v_cvt_pk_bf16_f32 v176, v160, v161
	v_cvt_pk_bf16_f32 v177, v64, v65
	v_cvt_pk_bf16_f32 v178, v68, v69
	v_cvt_pk_bf16_f32 v179, v66, v67
	v_exp_f32_e32 v70, v74
	v_exp_f32_e32 v71, v75
	s_waitcnt lgkmcnt(0)
	v_mfma_f32_32x32x16_bf16 v[16:31], v[136:139], v[176:179], v[16:31]
	v_exp_f32_e32 v136, v72
	v_exp_f32_e32 v137, v73
	v_exp_f32_e32 v74, v76
	v_exp_f32_e32 v75, v77
	v_exp_f32_e32 v72, v78
	v_exp_f32_e32 v73, v79
	v_exp_f32_e32 v76, v48
	v_mfma_f32_32x32x16_bf16 v[0:15], v[144:147], v[176:179], v[0:15]
	v_cvt_pk_bf16_f32 v144, v136, v137
	v_cvt_pk_bf16_f32 v145, v70, v71
	v_cvt_pk_bf16_f32 v146, v74, v75
	v_cvt_pk_bf16_f32 v147, v72, v73
	v_exp_f32_e32 v77, v49
	v_exp_f32_e32 v48, v50
	v_exp_f32_e32 v49, v51
	v_mfma_f32_32x32x16_bf16 v[16:31], v[124:127], v[144:147], v[16:31]
	v_exp_f32_e32 v52, v52
	v_exp_f32_e32 v53, v53
	v_exp_f32_e32 v50, v54
	v_exp_f32_e32 v51, v55
	v_cvt_pk_bf16_f32 v124, v76, v77
	v_cvt_pk_bf16_f32 v125, v48, v49
	v_cvt_pk_bf16_f32 v126, v52, v53
	v_mfma_f32_32x32x16_bf16 v[0:15], v[140:143], v[144:147], v[0:15]
	v_cvt_pk_bf16_f32 v127, v50, v51
	v_exp_f32_e32 v78, v56
	v_exp_f32_e32 v79, v57
	v_exp_f32_e32 v54, v58
	v_exp_f32_e32 v55, v59
	v_exp_f32_e32 v58, v60
	v_exp_f32_e32 v59, v61
	v_mfma_f32_32x32x16_bf16 v[16:31], v[132:135], v[124:127], v[16:31]
	v_exp_f32_e32 v56, v62
	v_exp_f32_e32 v57, v63
	v_cvt_pk_bf16_f32 v60, v78, v79
	v_cvt_pk_bf16_f32 v61, v54, v55
	v_cvt_pk_bf16_f32 v62, v58, v59
	v_cvt_pk_bf16_f32 v63, v56, v57
	v_mfma_f32_32x32x16_bf16 v[0:15], v[128:131], v[124:127], v[0:15]
	v_mfma_f32_32x32x16_bf16 v[16:31], v[120:123], v[60:63], v[16:31]
	v_mfma_f32_32x32x16_bf16 v[0:15], v[116:119], v[60:63], v[0:15]
	s_waitcnt vmcnt(0)
	ds_write2_b64 v247, v[112:113], v[114:115] offset1:2
	v_pk_add_f32 v[48:49], v[64:65], v[48:49]
	v_pk_add_f32 v[60:61], v[160:161], v[76:77]
	v_pk_add_f32 v[48:49], v[152:153], v[48:49]
	v_pk_add_f32 v[50:51], v[66:67], v[50:51]
	v_pk_add_f32 v[60:61], v[150:151], v[60:61]
	v_pk_add_f32 v[52:53], v[68:69], v[52:53]
	v_pk_add_f32 v[48:49], v[50:51], v[48:49]
	v_pk_add_f32 v[50:51], v[70:71], v[54:55]
	v_pk_add_f32 v[52:53], v[52:53], v[60:61]
	v_pk_add_f32 v[60:61], v[136:137], v[78:79]
	v_pk_add_f32 v[48:49], v[50:51], v[48:49]
	v_pk_add_f32 v[50:51], v[72:73], v[56:57]
	v_pk_add_f32 v[52:53], v[60:61], v[52:53]
	v_pk_add_f32 v[58:59], v[74:75], v[58:59]
	v_pk_add_f32 v[152:153], v[50:51], v[48:49]
	v_pk_add_f32 v[150:151], v[58:59], v[52:53]
	s_waitcnt lgkmcnt(0)
	s_barrier
; #define AT_QK_LD0(kb_) do { if constexpr (NEGM) { const LAS unsigned char* kbp_ = Kl + (kb_) * KBUF + r32 * KROWB + hi * 16; AT_KLD2(0); __builtin_amdgcn_sched_barrier(0); } } while (0)
; template <int DQK, int DV, int RH, bool NEGM> ...
;     ...
;         for (int t = 0; t < NT; ++t) {
;             const int kb = t & 1;
;             if (t + 1 < NT) AT_GLOAD(t + 1);
;             f32x16 p[RH][2];
;             AT_QK_LD0(kb); AT_QK(kb); AT_VLOAD(vs_cur); AT_SOFTMAX(); AT_PV(vs_cur);
;             if (t + 1 < NT) AT_LSTORE(kb ^ 1, vs_next);
;             __syncthreads();
;             vs_prev = vs_cur; vs_cur = vs_next; vs_next = (vs_next == 2) ? 0 : vs_next + 1;
	ds_read_b128 v[48:51], v169 offset:13312
	ds_read_b128 v[52:55], v169 offset:13344
	ds_read_b128 v[116:119], v169 offset:19968
	ds_read_b128 v[120:123], v169 offset:20000
	s_mov_b32 m0, s70
	s_nop 0
	global_load_lds_dwordx4 v241, s[98:99]
	s_mov_b32 m0, s73
	global_load_dwordx4 v[112:115], v158, s[100:101] offset:512
	global_load_lds_dwordx4 v242, s[98:99]
	s_add_u32 s98, s98, 0x18000
	s_addc_u32 s99, s99, 0
	s_waitcnt lgkmcnt(3)
	v_mfma_f32_32x32x16_bf16 v[64:79], v[48:51], v[100:103], v[32:47]
	ds_read_b128 v[124:127], v169 offset:13376
	ds_read_b128 v[128:131], v169 offset:13408
	ds_read_b128 v[132:135], v169 offset:20032
	ds_read_b128 v[136:139], v169 offset:20064
	s_waitcnt lgkmcnt(4)
	v_mfma_f32_32x32x16_bf16 v[64:79], v[52:55], v[96:99], v[64:79]
	v_mfma_f32_32x32x16_bf16 v[48:63], v[116:119], v[100:103], v[32:47]
	v_mfma_f32_32x32x16_bf16 v[48:63], v[120:123], v[96:99], v[48:63]
	s_waitcnt lgkmcnt(1)
	v_mfma_f32_32x32x16_bf16 v[64:79], v[124:127], v[92:95], v[64:79]
	v_mfma_f32_32x32x16_bf16 v[48:63], v[132:135], v[92:95], v[48:63]
	v_mfma_f32_32x32x16_bf16 v[64:79], v[128:131], v[88:91], v[64:79]
	ds_read_b128 v[116:119], v169 offset:13440
	ds_read_b128 v[120:123], v169 offset:13472
	ds_read_b128 v[128:131], v169 offset:20096
	ds_read_b128 v[176:179], v169 offset:20128
	s_waitcnt lgkmcnt(3)
	v_mfma_f32_32x32x16_bf16 v[48:63], v[136:139], v[88:91], v[48:63]
	v_mfma_f32_32x32x16_bf16 v[64:79], v[116:119], v[84:87], v[64:79]
	ds_read_b128 v[136:139], v170 offset:45056
	ds_read_b128 v[124:127], v170 offset:45088
	s_waitcnt lgkmcnt(3)
	v_mfma_f32_32x32x16_bf16 v[48:63], v[128:131], v[84:87], v[48:63]
	v_mfma_f32_32x32x16_bf16 v[64:79], v[120:123], v[80:83], v[64:79]
	ds_read_b128 v[132:135], v170 offset:45120
	ds_read_b128 v[120:123], v170 offset:45152
	ds_read_b128 v[144:147], v170 offset:49664
	ds_read_b128 v[140:143], v170 offset:49696
	ds_read_b128 v[128:131], v170 offset:49728
	ds_read_b128 v[116:119], v170 offset:49760
	s_waitcnt lgkmcnt(8)
	v_mfma_f32_32x32x16_bf16 v[48:63], v[176:179], v[80:83], v[48:63]
	s_add_i32 s43, s43, 1
	s_nop 3
	v_exp_f32_e32 v160, v64
	v_exp_f32_e32 v161, v65
	v_exp_f32_e32 v64, v66
	v_exp_f32_e32 v65, v67
	v_exp_f32_e32 v68, v68
	v_exp_f32_e32 v69, v69
	v_exp_f32_e32 v66, v70
	v_exp_f32_e32 v67, v71
	v_cvt_pk_bf16_f32 v176, v160, v161
	v_cvt_pk_bf16_f32 v177, v64, v65
	v_cvt_pk_bf16_f32 v178, v68, v69
	v_cvt_pk_bf16_f32 v179, v66, v67
	v_exp_f32_e32 v70, v74
	v_exp_f32_e32 v71, v75
	s_waitcnt lgkmcnt(0)
	v_mfma_f32_32x32x16_bf16 v[16:31], v[136:139], v[176:179], v[16:31]
	v_exp_f32_e32 v136, v72
	v_exp_f32_e32 v137, v73
	v_exp_f32_e32 v74, v76
	v_exp_f32_e32 v75, v77
	v_exp_f32_e32 v72, v78
	v_exp_f32_e32 v73, v79
	v_exp_f32_e32 v76, v48
	v_mfma_f32_32x32x16_bf16 v[0:15], v[144:147], v[176:179], v[0:15]
	v_cvt_pk_bf16_f32 v144, v136, v137
	v_cvt_pk_bf16_f32 v145, v70, v71
	v_cvt_pk_bf16_f32 v146, v74, v75
	v_cvt_pk_bf16_f32 v147, v72, v73
	v_exp_f32_e32 v77, v49
	v_exp_f32_e32 v48, v50
	v_exp_f32_e32 v49, v51
	v_mfma_f32_32x32x16_bf16 v[16:31], v[124:127], v[144:147], v[16:31]
	v_exp_f32_e32 v52, v52
	v_exp_f32_e32 v53, v53
	v_exp_f32_e32 v50, v54
	v_exp_f32_e32 v51, v55
	v_cvt_pk_bf16_f32 v124, v76, v77
	v_cvt_pk_bf16_f32 v125, v48, v49
	v_cvt_pk_bf16_f32 v126, v52, v53
	v_mfma_f32_32x32x16_bf16 v[0:15], v[140:143], v[144:147], v[0:15]
	v_cvt_pk_bf16_f32 v127, v50, v51
	v_exp_f32_e32 v78, v56
	v_exp_f32_e32 v79, v57
	v_exp_f32_e32 v54, v58
	v_exp_f32_e32 v55, v59
	v_exp_f32_e32 v58, v60
	v_exp_f32_e32 v59, v61
	v_mfma_f32_32x32x16_bf16 v[16:31], v[132:135], v[124:127], v[16:31]
	v_exp_f32_e32 v56, v62
	v_exp_f32_e32 v57, v63
	v_cvt_pk_bf16_f32 v60, v78, v79
	v_cvt_pk_bf16_f32 v61, v54, v55
	v_cvt_pk_bf16_f32 v62, v58, v59
	v_cvt_pk_bf16_f32 v63, v56, v57
	v_mfma_f32_32x32x16_bf16 v[0:15], v[128:131], v[124:127], v[0:15]
	v_mfma_f32_32x32x16_bf16 v[16:31], v[120:123], v[60:63], v[16:31]
	v_mfma_f32_32x32x16_bf16 v[0:15], v[116:119], v[60:63], v[0:15]
	s_waitcnt vmcnt(0)
	ds_write2_b64 v243, v[112:113], v[114:115] offset1:2
	v_pk_add_f32 v[48:49], v[64:65], v[48:49]
	v_pk_add_f32 v[60:61], v[160:161], v[76:77]
	v_pk_add_f32 v[48:49], v[152:153], v[48:49]
	v_pk_add_f32 v[50:51], v[66:67], v[50:51]
	v_pk_add_f32 v[60:61], v[150:151], v[60:61]
	v_pk_add_f32 v[52:53], v[68:69], v[52:53]
	v_pk_add_f32 v[48:49], v[50:51], v[48:49]
	v_pk_add_f32 v[50:51], v[70:71], v[54:55]
	v_pk_add_f32 v[52:53], v[52:53], v[60:61]
	v_pk_add_f32 v[60:61], v[136:137], v[78:79]
	v_pk_add_f32 v[48:49], v[50:51], v[48:49]
	v_pk_add_f32 v[50:51], v[72:73], v[56:57]
	v_pk_add_f32 v[52:53], v[60:61], v[52:53]
	v_pk_add_f32 v[58:59], v[74:75], v[58:59]
	v_pk_add_f32 v[152:153], v[50:51], v[48:49]
	v_pk_add_f32 v[150:151], v[58:59], v[52:53]
	s_waitcnt lgkmcnt(0)
	s_barrier
; #define AT_QK_LD0(kb_) do { if constexpr (NEGM) { const LAS unsigned char* kbp_ = Kl + (kb_) * KBUF + r32 * KROWB + hi * 16; AT_KLD2(0); __builtin_amdgcn_sched_barrier(0); } } while (0)
; template <int DQK, int DV, int RH, bool NEGM> ...
;     ...
;         for (int t = 0; t < NT; ++t) {
;             const int kb = t & 1;
;             if (t + 1 < NT) AT_GLOAD(t + 1);
;             f32x16 p[RH][2];
;             AT_QK_LD0(kb); AT_QK(kb); AT_VLOAD(vs_cur); AT_SOFTMAX(); AT_PV(vs_cur);
;             if (t + 1 < NT) AT_LSTORE(kb ^ 1, vs_next);
;             __syncthreads();
;             vs_prev = vs_cur; vs_cur = vs_next; vs_next = (vs_next == 2) ? 0 : vs_next + 1;
;         }
	ds_read_b128 v[48:51], v169
	ds_read_b128 v[52:55], v169 offset:32
	ds_read_b128 v[116:119], v169 offset:6656
	ds_read_b128 v[120:123], v169 offset:6688
	s_add_i32 m0, s70, 13312
	s_nop 0
	global_load_lds_dwordx4 v241, s[98:99]
	s_add_i32 m0, s73, s74
	global_load_dwordx4 v[112:115], v158, s[100:101] offset:640
	global_load_lds_dwordx4 v242, s[98:99]
	s_add_u32 s98, s98, 0x18000
	s_addc_u32 s99, s99, 0
	s_waitcnt lgkmcnt(3)
	v_mfma_f32_32x32x16_bf16 v[64:79], v[48:51], v[100:103], v[32:47]
	ds_read_b128 v[124:127], v169 offset:64
	ds_read_b128 v[128:131], v169 offset:96
	ds_read_b128 v[132:135], v169 offset:6720
	ds_read_b128 v[136:139], v169 offset:6752
	s_waitcnt lgkmcnt(4)
	v_mfma_f32_32x32x16_bf16 v[64:79], v[52:55], v[96:99], v[64:79]
	v_mfma_f32_32x32x16_bf16 v[48:63], v[116:119], v[100:103], v[32:47]
	v_mfma_f32_32x32x16_bf16 v[48:63], v[120:123], v[96:99], v[48:63]
	s_waitcnt lgkmcnt(1)
	v_mfma_f32_32x32x16_bf16 v[64:79], v[124:127], v[92:95], v[64:79]
	v_mfma_f32_32x32x16_bf16 v[48:63], v[132:135], v[92:95], v[48:63]
	v_mfma_f32_32x32x16_bf16 v[64:79], v[128:131], v[88:91], v[64:79]
	ds_read_b128 v[116:119], v169 offset:128
	ds_read_b128 v[120:123], v169 offset:160
	ds_read_b128 v[128:131], v169 offset:6784
	ds_read_b128 v[176:179], v169 offset:6816
	s_waitcnt lgkmcnt(3)
	v_mfma_f32_32x32x16_bf16 v[48:63], v[136:139], v[88:91], v[48:63]
	v_mfma_f32_32x32x16_bf16 v[64:79], v[116:119], v[84:87], v[64:79]
	ds_read_b128 v[136:139], v170 offset:26624
	ds_read_b128 v[124:127], v170 offset:26656
	s_waitcnt lgkmcnt(3)
	v_mfma_f32_32x32x16_bf16 v[48:63], v[128:131], v[84:87], v[48:63]
	v_mfma_f32_32x32x16_bf16 v[64:79], v[120:123], v[80:83], v[64:79]
	ds_read_b128 v[132:135], v170 offset:26688
	ds_read_b128 v[120:123], v170 offset:26720
	ds_read_b128 v[144:147], v170 offset:31232
	ds_read_b128 v[140:143], v170 offset:31264
	ds_read_b128 v[128:131], v170 offset:31296
	ds_read_b128 v[116:119], v170 offset:31328
	s_waitcnt lgkmcnt(8)
	v_mfma_f32_32x32x16_bf16 v[48:63], v[176:179], v[80:83], v[48:63]
	s_add_i32 s43, s43, 1
	s_nop 3
	v_exp_f32_e32 v160, v64
	v_exp_f32_e32 v161, v65
	v_exp_f32_e32 v64, v66
	v_exp_f32_e32 v65, v67
	v_exp_f32_e32 v68, v68
	v_exp_f32_e32 v69, v69
	v_exp_f32_e32 v66, v70
	v_exp_f32_e32 v67, v71
	v_cvt_pk_bf16_f32 v176, v160, v161
	v_cvt_pk_bf16_f32 v177, v64, v65
	v_cvt_pk_bf16_f32 v178, v68, v69
	v_cvt_pk_bf16_f32 v179, v66, v67
	v_exp_f32_e32 v70, v74
	v_exp_f32_e32 v71, v75
	s_waitcnt lgkmcnt(0)
	v_mfma_f32_32x32x16_bf16 v[16:31], v[136:139], v[176:179], v[16:31]
	v_exp_f32_e32 v136, v72
	v_exp_f32_e32 v137, v73
	v_exp_f32_e32 v74, v76
	v_exp_f32_e32 v75, v77
	v_exp_f32_e32 v72, v78
	v_exp_f32_e32 v73, v79
	v_exp_f32_e32 v76, v48
	v_mfma_f32_32x32x16_bf16 v[0:15], v[144:147], v[176:179], v[0:15]
	v_cvt_pk_bf16_f32 v144, v136, v137
	v_cvt_pk_bf16_f32 v145, v70, v71
	v_cvt_pk_bf16_f32 v146, v74, v75
	v_cvt_pk_bf16_f32 v147, v72, v73
	v_exp_f32_e32 v77, v49
	v_exp_f32_e32 v48, v50
	v_exp_f32_e32 v49, v51
	v_mfma_f32_32x32x16_bf16 v[16:31], v[124:127], v[144:147], v[16:31]
	v_exp_f32_e32 v52, v52
	v_exp_f32_e32 v53, v53
	v_exp_f32_e32 v50, v54
	v_exp_f32_e32 v51, v55
	v_cvt_pk_bf16_f32 v124, v76, v77
	v_cvt_pk_bf16_f32 v125, v48, v49
	v_cvt_pk_bf16_f32 v126, v52, v53
	v_mfma_f32_32x32x16_bf16 v[0:15], v[140:143], v[144:147], v[0:15]
	v_cvt_pk_bf16_f32 v127, v50, v51
	v_exp_f32_e32 v78, v56
	v_exp_f32_e32 v79, v57
	v_exp_f32_e32 v54, v58
	v_exp_f32_e32 v55, v59
	v_exp_f32_e32 v58, v60
	v_exp_f32_e32 v59, v61
	v_mfma_f32_32x32x16_bf16 v[16:31], v[132:135], v[124:127], v[16:31]
	v_exp_f32_e32 v56, v62
	v_exp_f32_e32 v57, v63
	v_cvt_pk_bf16_f32 v60, v78, v79
	v_cvt_pk_bf16_f32 v61, v54, v55
	v_cvt_pk_bf16_f32 v62, v58, v59
	v_cvt_pk_bf16_f32 v63, v56, v57
	v_mfma_f32_32x32x16_bf16 v[0:15], v[128:131], v[124:127], v[0:15]
	v_mfma_f32_32x32x16_bf16 v[16:31], v[120:123], v[60:63], v[16:31]
	v_mfma_f32_32x32x16_bf16 v[0:15], v[116:119], v[60:63], v[0:15]
	s_waitcnt vmcnt(0)
	ds_write2_b64 v246, v[112:113], v[114:115] offset1:2
	v_pk_add_f32 v[48:49], v[64:65], v[48:49]
	v_pk_add_f32 v[60:61], v[160:161], v[76:77]
	v_pk_add_f32 v[48:49], v[152:153], v[48:49]
	v_pk_add_f32 v[50:51], v[66:67], v[50:51]
	v_pk_add_f32 v[60:61], v[150:151], v[60:61]
	v_pk_add_f32 v[52:53], v[68:69], v[52:53]
	v_pk_add_f32 v[48:49], v[50:51], v[48:49]
	v_pk_add_f32 v[50:51], v[70:71], v[54:55]
	v_pk_add_f32 v[52:53], v[52:53], v[60:61]
	v_pk_add_f32 v[60:61], v[136:137], v[78:79]
	v_pk_add_f32 v[48:49], v[50:51], v[48:49]
	v_pk_add_f32 v[50:51], v[72:73], v[56:57]
	v_pk_add_f32 v[52:53], v[60:61], v[52:53]
	v_pk_add_f32 v[58:59], v[74:75], v[58:59]
	v_pk_add_f32 v[152:153], v[50:51], v[48:49]
	v_pk_add_f32 v[150:151], v[58:59], v[52:53]
	v_max3_f32 v148, v150, v151, v152
	v_max_f32_e32 v148, v148, v153
	v_cmp_nge_f32_e32 vcc, 0x49800000, v148
	s_cbranch_vccnz .Lmla_renorm
.Lmla_renorm_back:
	s_add_u32 s100, s100, 0x300
	s_addc_u32 s101, s101, 0
	s_waitcnt lgkmcnt(0)
	s_branch .Lmla_loop
